# attn_item softmax: max-subtraction folded into QK MFMA C-init, scalar adds for rowsum, hand-interleaved exp/cvt/PV
# speedup vs baseline: 1.0170x; 1.0165x over previous
; __device__ __forceinline__ float bflo(unsigned u) { return __uint_as_float(u << 16); }
; __device__ __forceinline__ float bfhi(unsigned u) { return __uint_as_float(u & 0xffff0000u); }
; __device__ __forceinline__ void rope_cs(int pos, int i, float& c, float& s) {
;     const double rev = (double)pos * INVF[i] * 0.15915494309189535;
;     const float fr = (float)(rev - floor(rev));
;     c = __builtin_amdgcn_cosf(fr); s = __builtin_amdgcn_sinf(fr);
; __device__ __forceinline__ void q_prologue(const Params& p, int l, int qrow, int pos, int h, int hf, int lane, bf16x8 (&qf)[6]) {
;     ...
;     const bf16_t* qp = qraw + (size_t)qrow * 768 + h * DQK + 8 * hf;
;     float v[6][8];
; #pragma unroll
;     for (int s = 0; s < 6; ++s) { const u32x4 raw = *(const u32x4*)(qp + 16 * s);
;         v[s][0] = bflo(raw.x); v[s][1] = bfhi(raw.x); v[s][2] = bflo(raw.y); v[s][3] = bfhi(raw.y); v[s][4] = bflo(raw.z); v[s][5] = bfhi(raw.z); v[s][6] = bflo(raw.w); v[s][7] = bfhi(raw.w); }
; #pragma unroll
;     for (int e = 0; e < 8; ++e) { float c, s; rope_cs(pos, 8 * hf + e, c, s); const float x1 = v[4][e], x2 = v[5][e]; v[4][e] = x1 * c - x2 * s; v[5][e] = x1 * s + x2 * c; }
.LBB0_610:
	s_or_b64 exec, exec, s[48:49]
	s_bitcmp0_b32 s9, 0
	s_cselect_b32 s5, s16, s17
	s_ashr_i32 s10, s10, 6
	s_lshl_b32 s11, s5, 3
	s_movk_i32 s12, 0xd0
	v_and_b32_e32 v52, 63, v136
	v_and_b32_e32 v59, 31, v136
	v_bfe_u32 v246, v136, 5, 1
	s_add_i32 s10, s11, s10
	v_mad_u64_u32 v[234:235], s[12:13], v56, s12, v[0:1]
	v_mul_u32_u24_e32 v139, 0xd0, v138
	s_lshl_b32 s11, s10, 5
	v_add_u32_e32 v2, 16, v59
	s_add_i32 s12, s11, s20
	v_add_u32_e32 v232, s12, v2
	v_add_u32_e32 v26, s11, v2
	v_mov_b64_e32 v[2:3], s[24:25]
	s_movk_i32 s11, 0x600
	v_mad_i64_i32 v[2:3], s[12:13], v232, s11, v[2:3]
	v_lshlrev_b32_e32 v236, 4, v246
	v_mov_b32_e32 v237, v1
	v_lshl_add_u64 v[18:19], v[2:3], 0, v[236:237]
	v_lshlrev_b32_e32 v36, 6, v246
	s_getpc_b64 s[12:13]
	s_add_u32 s12, s12, _ZL4INVF@rel32@lo+4
	s_addc_u32 s13, s13, _ZL4INVF@rel32@hi+12
	global_load_dwordx4 v[2:5], v[18:19], off
	global_load_dwordx4 v[6:9], v[18:19], off offset:32
	global_load_dwordx4 v[10:13], v[18:19], off offset:64
	global_load_dwordx4 v[14:17], v[18:19], off offset:96
	global_load_dwordx4 v[22:25], v[18:19], off offset:128
	s_nop 0
	global_load_dwordx4 v[18:21], v[18:19], off offset:160
	v_cvt_f64_i32_e32 v[34:35], v26
	global_load_dwordx4 v[26:29], v36, s[12:13] offset:48
	global_load_dwordx4 v[30:33], v36, s[12:13] offset:32
	global_load_dwordx4 v[42:45], v36, s[12:13] offset:16
	global_load_dwordx4 v[38:41], v36, s[12:13]
	v_and_b32_e32 v126, 32, v136
	s_movk_i32 s11, 0x90
	v_mad_u64_u32 v[238:239], s[12:13], v56, s11, v[0:1]
	v_add_u32_e32 v0, 0, v238
	s_waitcnt vmcnt(9)
	v_lshlrev_b32_e32 v128, 16, v2
	s_waitcnt vmcnt(8)
	v_lshlrev_b32_e32 v92, 16, v9
	s_waitcnt vmcnt(7)
	v_lshlrev_b32_e32 v84, 16, v13
	s_waitcnt vmcnt(6)
	v_lshlrev_b32_e32 v82, 16, v14
	s_waitcnt vmcnt(3)
	v_mul_f64 v[26:27], v[26:27], v[34:35]
	s_waitcnt vmcnt(2)
	v_mul_f64 v[30:31], v[30:31], v[34:35]
	s_waitcnt vmcnt(1)
	v_mul_f64 v[44:45], v[44:45], v[34:35]
	s_waitcnt vmcnt(0)
	v_mul_f64 v[40:41], v[40:41], v[34:35]
	v_mul_f64 v[36:37], v[38:39], v[34:35]
	v_mul_f64 v[46:47], v[40:41], s[22:23]
	v_mul_f64 v[38:39], v[36:37], s[22:23]
	v_floor_f64_e32 v[46:47], v[46:47]
	v_floor_f64_e32 v[38:39], v[38:39]
	v_fma_f64 v[40:41], v[40:41], s[22:23], -v[46:47]
	v_fma_f64 v[36:37], v[36:37], s[22:23], -v[38:39]
	v_cvt_f32_f64_e32 v39, v[40:41]
	v_mul_f64 v[40:41], v[42:43], v[34:35]
	v_mul_f64 v[46:47], v[44:45], s[22:23]
	v_mul_f64 v[42:43], v[40:41], s[22:23]
	v_floor_f64_e32 v[46:47], v[46:47]
	v_floor_f64_e32 v[42:43], v[42:43]
	v_fma_f64 v[44:45], v[44:45], s[22:23], -v[46:47]
	v_fma_f64 v[40:41], v[40:41], s[22:23], -v[42:43]
	v_cvt_f32_f64_e32 v43, v[44:45]
	v_mul_f64 v[44:45], v[30:31], s[22:23]
	v_floor_f64_e32 v[44:45], v[44:45]
	v_fma_f64 v[30:31], v[30:31], s[22:23], -v[44:45]
	v_cvt_f32_f64_e32 v30, v[30:31]
	v_cos_f32_e32 v44, v30
	v_sin_f32_e32 v46, v30
	v_mul_f64 v[30:31], v[32:33], v[34:35]
	v_mul_f64 v[32:33], v[30:31], s[22:23]
	v_floor_f64_e32 v[32:33], v[32:33]
	v_fma_f64 v[30:31], v[30:31], s[22:23], -v[32:33]
	v_cvt_f32_f64_e32 v30, v[30:31]
	v_cos_f32_e32 v45, v30
	v_sin_f32_e32 v47, v30
	v_mul_f64 v[30:31], v[26:27], s[22:23]
	v_floor_f64_e32 v[30:31], v[30:31]
	v_fma_f64 v[26:27], v[26:27], s[22:23], -v[30:31]
	v_cvt_f32_f64_e32 v26, v[26:27]
	v_cos_f32_e32 v48, v26
	v_sin_f32_e32 v50, v26
	v_mul_f64 v[26:27], v[28:29], v[34:35]
	v_mul_f64 v[28:29], v[26:27], s[22:23]
	v_floor_f64_e32 v[28:29], v[28:29]
	v_fma_f64 v[26:27], v[26:27], s[22:23], -v[28:29]
	v_cvt_f32_f64_e32 v37, v[36:37]
	v_cvt_f32_f64_e32 v41, v[40:41]
	v_cvt_f32_f64_e32 v26, v[26:27]
	v_cos_f32_e32 v36, v37
	v_sin_f32_e32 v38, v37
	v_cos_f32_e32 v37, v39
	v_cos_f32_e32 v40, v41
	v_sin_f32_e32 v42, v41
	v_cos_f32_e32 v41, v43
	v_cos_f32_e32 v49, v26
	v_sin_f32_e32 v39, v39
	v_sin_f32_e32 v43, v43
	v_sin_f32_e32 v51, v26
	v_lshlrev_b32_e32 v72, 16, v20
	v_and_b32_e32 v73, 0xffff0000, v20
	v_lshlrev_b32_e32 v26, 2, v52
	v_lshlrev_b32_e32 v54, 16, v21
	v_and_b32_e32 v55, 0xffff0000, v21
	v_lshlrev_b32_e32 v70, 16, v24
	v_and_b32_e32 v71, 0xffff0000, v24
	v_pk_mul_f32 v[20:21], v[44:45], v[72:73]
	v_lshlrev_b32_e32 v76, 16, v19
	v_and_b32_e32 v77, 0xffff0000, v19
	v_lshlrev_b32_e32 v80, 16, v18
	v_and_b32_e32 v81, 0xffff0000, v18
	v_xor_b32_e32 v235, 0x80, v26
	v_lshlrev_b32_e32 v52, 16, v25
	v_and_b32_e32 v53, 0xffff0000, v25
	v_pk_mul_f32 v[26:27], v[48:49], v[54:55]
	v_pk_fma_f32 v[62:63], v[46:47], v[70:71], v[20:21]
	v_lshlrev_b32_e32 v74, 16, v23
	v_and_b32_e32 v75, 0xffff0000, v23
	v_pk_mul_f32 v[20:21], v[40:41], v[76:77]
	v_lshlrev_b32_e32 v78, 16, v22
	v_and_b32_e32 v79, 0xffff0000, v22
	v_pk_mul_f32 v[18:19], v[36:37], v[80:81]
	v_pk_fma_f32 v[60:61], v[50:51], v[52:53], v[26:27]
	v_pk_fma_f32 v[64:65], v[42:43], v[74:75], v[20:21]
	v_pk_fma_f32 v[22:23], v[38:39], v[78:79], v[18:19]
	v_pk_mul_f32 v[50:51], v[50:51], v[54:55]
	v_pk_mul_f32 v[46:47], v[46:47], v[72:73]
	v_pk_mul_f32 v[42:43], v[42:43], v[76:77]
	v_pk_mul_f32 v[38:39], v[38:39], v[80:81]
	global_load_dwordx4 v[24:27], v126, s[30:31] offset:336
	global_load_dwordx4 v[28:31], v126, s[30:31] offset:320
	global_load_dwordx4 v[18:21], v126, s[30:31] offset:272
	global_load_dwordx4 v[32:35], v126, s[30:31] offset:256
	v_pk_fma_f32 v[68:69], v[48:49], v[52:53], v[50:51] neg_lo:[0,0,1] neg_hi:[0,0,1]
	v_pk_fma_f32 v[70:71], v[44:45], v[70:71], v[46:47] neg_lo:[0,0,1] neg_hi:[0,0,1]
	v_pk_fma_f32 v[72:73], v[40:41], v[74:75], v[42:43] neg_lo:[0,0,1] neg_hi:[0,0,1]
	v_pk_fma_f32 v[74:75], v[36:37], v[78:79], v[38:39] neg_lo:[0,0,1] neg_hi:[0,0,1]
	v_lshlrev_b32_e32 v76, 16, v17
	v_and_b32_e32 v77, 0xffff0000, v17
	global_load_dwordx4 v[36:39], v126, s[30:31] offset:208
; #define LAS __attribute__((address_space(3)))
; __device__ __forceinline__ float shx32(float v, int lane) { return __int_as_float(__builtin_amdgcn_ds_bpermute((lane ^ 32) << 2, __float_as_int(v))); }
; __device__ __forceinline__ void q_prologue(const Params& p, int l, int qrow, int pos, int h, int hf, int lane, bf16x8 (&qf)[6]) {
;     ...
;     float ss = 0.f;
; #pragma unroll
;     for (int s = 0; s < 6; ++s)
; #pragma unroll
;         for (int e = 0; e < 8; ++e) ss += v[s][e] * v[s][e];
;     ss += shx32(ss, lane);
; __device__ __forceinline__ void attn_item(const Params& p, int l, LAS unsigned char* lds, int b, int h, int J) {
;     ...
;     u32x4 skn = *(const u32x4*)gkn, svt = *(const u32x4*)gvt, skr = {0u, 0u, 0u, 0u};
;     if (has_kr) skr = *(const u32x4*)gkr;
;     __builtin_amdgcn_sched_barrier(0);
;     bf16x8 qf[6];
;     q_prologue(p, l, qrow0 + r, NMETA + 32 * i + r, h, hf, lane, qf);
;     *(LAS u32x4*)(lds + wkn) = skn; *(LAS u32x4*)(lds + wvt) = svt; if (has_kr) *(LAS u32x4*)(lds + wkr) = skr;
;     __syncthreads();
	global_load_dwordx4 v[40:43], v126, s[30:31] offset:192
	v_lshlrev_b32_e32 v78, 16, v16
	v_and_b32_e32 v79, 0xffff0000, v16
	v_lshlrev_b32_e32 v80, 16, v15
	v_and_b32_e32 v81, 0xffff0000, v15
	v_and_b32_e32 v83, 0xffff0000, v14
	v_and_b32_e32 v85, 0xffff0000, v13
	global_load_dwordx4 v[14:17], v126, s[30:31] offset:144
	global_load_dwordx4 v[44:47], v126, s[30:31] offset:128
	v_lshlrev_b32_e32 v86, 16, v12
	v_and_b32_e32 v87, 0xffff0000, v12
	v_lshlrev_b32_e32 v88, 16, v11
	v_and_b32_e32 v89, 0xffff0000, v11
	v_lshlrev_b32_e32 v90, 16, v10
	v_and_b32_e32 v91, 0xffff0000, v10
	v_and_b32_e32 v93, 0xffff0000, v9
	global_load_dwordx4 v[10:13], v126, s[30:31] offset:80
	global_load_dwordx4 v[48:51], v126, s[30:31] offset:64
	v_lshlrev_b32_e32 v96, 16, v8
	v_and_b32_e32 v97, 0xffff0000, v8
	v_lshlrev_b32_e32 v116, 16, v7
	v_and_b32_e32 v117, 0xffff0000, v7
	v_lshlrev_b32_e32 v114, 16, v6
	v_and_b32_e32 v115, 0xffff0000, v6
	global_load_dwordx4 v[6:9], v126, s[30:31] offset:16
	global_load_dwordx4 v[52:55], v126, s[30:31]
	v_and_b32_e32 v129, 0xffff0000, v2
	v_lshlrev_b32_e32 v118, 16, v5
	v_and_b32_e32 v119, 0xffff0000, v5
	v_lshlrev_b32_e32 v126, 16, v4
	v_and_b32_e32 v127, 0xffff0000, v4
	v_lshlrev_b32_e32 v4, 16, v3
	v_and_b32_e32 v5, 0xffff0000, v3
	v_pk_mul_f32 v[2:3], v[128:129], v[128:129]
	v_pk_mul_f32 v[166:167], v[4:5], v[4:5]
	v_add_f32_e32 v2, v2, v3
	v_add_f32_e32 v2, v166, v2
	v_pk_mul_f32 v[164:165], v[126:127], v[126:127]
	v_add_f32_e32 v2, v167, v2
	v_add_f32_e32 v2, v164, v2
	v_pk_mul_f32 v[162:163], v[118:119], v[118:119]
	v_add_f32_e32 v2, v165, v2
	v_add_f32_e32 v2, v162, v2
	v_pk_mul_f32 v[160:161], v[114:115], v[114:115]
	v_add_f32_e32 v2, v163, v2
	v_add_f32_e32 v2, v160, v2
	v_pk_mul_f32 v[158:159], v[116:117], v[116:117]
	v_add_f32_e32 v2, v161, v2
	v_add_f32_e32 v2, v158, v2
	v_pk_mul_f32 v[156:157], v[96:97], v[96:97]
	v_add_f32_e32 v2, v159, v2
	v_add_f32_e32 v2, v156, v2
	v_pk_mul_f32 v[154:155], v[92:93], v[92:93]
	v_add_f32_e32 v2, v157, v2
	v_add_f32_e32 v2, v154, v2
	v_pk_mul_f32 v[152:153], v[90:91], v[90:91]
	v_add_f32_e32 v2, v155, v2
	v_add_f32_e32 v2, v152, v2
	v_pk_mul_f32 v[150:151], v[88:89], v[88:89]
	v_add_f32_e32 v2, v153, v2
	v_add_f32_e32 v2, v150, v2
	v_pk_mul_f32 v[148:149], v[86:87], v[86:87]
	v_add_f32_e32 v2, v151, v2
	v_add_f32_e32 v2, v148, v2
	v_pk_mul_f32 v[146:147], v[84:85], v[84:85]
	v_add_f32_e32 v2, v149, v2
	v_add_f32_e32 v2, v146, v2
	v_pk_mul_f32 v[144:145], v[82:83], v[82:83]
	v_add_f32_e32 v2, v147, v2
	v_add_f32_e32 v2, v144, v2
	v_pk_mul_f32 v[142:143], v[80:81], v[80:81]
	v_add_f32_e32 v2, v145, v2
	v_add_f32_e32 v2, v142, v2
	v_pk_mul_f32 v[140:141], v[78:79], v[78:79]
	v_add_f32_e32 v2, v143, v2
	v_add_f32_e32 v2, v140, v2
	v_pk_mul_f32 v[132:133], v[76:77], v[76:77]
	v_add_f32_e32 v2, v141, v2
	v_add_f32_e32 v2, v132, v2
	v_pk_mul_f32 v[130:131], v[74:75], v[74:75]
	v_add_f32_e32 v2, v133, v2
	v_add_f32_e32 v2, v130, v2
	v_pk_mul_f32 v[124:125], v[72:73], v[72:73]
	v_add_f32_e32 v2, v131, v2
	v_add_f32_e32 v2, v124, v2
	v_pk_mul_f32 v[122:123], v[70:71], v[70:71]
	v_add_f32_e32 v2, v125, v2
	v_add_f32_e32 v2, v122, v2
	v_pk_mul_f32 v[120:121], v[68:69], v[68:69]
	v_add_f32_e32 v2, v123, v2
	v_add_f32_e32 v2, v120, v2
	v_pk_mul_f32 v[112:113], v[22:23], v[22:23]
	v_add_f32_e32 v2, v121, v2
	v_add_f32_e32 v2, v112, v2
	v_pk_mul_f32 v[110:111], v[64:65], v[64:65]
	v_add_f32_e32 v2, v113, v2
	v_add_f32_e32 v2, v110, v2
	v_pk_mul_f32 v[94:95], v[62:63], v[62:63]
	v_add_f32_e32 v2, v111, v2
	v_add_f32_e32 v2, v94, v2
	v_pk_mul_f32 v[66:67], v[60:61], v[60:61]
	v_add_f32_e32 v2, v95, v2
	v_add_f32_e32 v2, v66, v2
	v_add_f32_e32 v2, v67, v2
	ds_bpermute_b32 v3, v235, v2
	v_add_u32_e32 v66, 0, v234
	ds_write_b128 v66, v[98:101]
	ds_write_b128 v0, v[102:105] offset:13312
	s_and_saveexec_b64 s[48:49], s[40:41]
	v_add3_u32 v0, v58, v139, 0
	ds_write_b128 v0, v[106:109] offset:128
	s_or_b64 exec, exec, s[48:49]
	s_cmp_lt_i32 s5, -1
	s_waitcnt lgkmcnt(0)
	s_barrier
	s_cbranch_scc1 .LBB0_606
; __device__ __forceinline__ unsigned pk2(float a, float b) { f32x2 v = {a, b}; bf16x2_t r = __builtin_convertvector(v, bf16x2_t); return __builtin_bit_cast(unsigned, r); }
; __device__ __forceinline__ void q_prologue(const Params& p, int l, int qrow, int pos, int h, int hf, int lane, bf16x8 (&qf)[6]) {
;     ...
;     const float rs = rsqrtf(ss * (1.f / DQK) + EPS) * 0.14724444602590306f;
; #pragma unroll
;     for (int s = 0; s < 6; ++s) { const float* g = qn + 16 * s + 8 * hf; u32x4 w;
;         w.x = pk2(v[s][0] * rs * g[0], v[s][1] * rs * g[1]); w.y = pk2(v[s][2] * rs * g[2], v[s][3] * rs * g[3]);
;         w.z = pk2(v[s][4] * rs * g[4], v[s][5] * rs * g[5]); w.w = pk2(v[s][6] * rs * g[6], v[s][7] * rs * g[7]);
;         qf[s] = __builtin_bit_cast(bf16x8, w); }
; __device__ __forceinline__ void attn_item(const Params& p, int l, LAS unsigned char* lds, int b, int h, int J) {
;     ...
;     f32x16 o0, o1;
; #pragma unroll
;     for (int q = 0; q < 16; ++q) { o0[q] = 0.f; o1[q] = 0.f; }
;     float mrun = -INFINITY, lsum = 0.f;
	v_add_f32_e32 v0, v2, v3
	v_fmamk_f32 v0, v0, 0x3c2aaaab, v210
	v_mul_f32_e32 v2, 0x4b800000, v0
	v_cmp_gt_f32_e32 vcc, s95, v0
	s_movk_i32 s12, 0x70
	s_ashr_i32 s10, s10, 1
	v_cndmask_b32_e32 v0, v0, v2, vcc
	v_rsq_f32_e32 v0, v0
	s_lshl_b32 s5, s5, 2
	s_add_i32 s11, s10, 2
	s_add_i32 s5, s5, 5
	v_mul_f32_e32 v2, 0x45800000, v0
	v_cndmask_b32_e32 v0, v0, v2, vcc
	v_mul_f32_e32 v0, 0x3e16c740, v0
	v_pk_mul_f32 v[2:3], v[0:1], v[128:129] op_sel_hi:[0,1]
	s_waitcnt vmcnt(0)
	v_pk_mul_f32 v[2:3], v[52:53], v[2:3]
	v_pk_mul_f32 v[4:5], v[0:1], v[4:5] op_sel_hi:[0,1]
	v_cvt_pk_bf16_f32 v110, v2, v3
	v_pk_mul_f32 v[2:3], v[0:1], v[126:127] op_sel_hi:[0,1]
	v_pk_mul_f32 v[2:3], v[6:7], v[2:3]
	v_pk_mul_f32 v[4:5], v[54:55], v[4:5]
	v_cvt_pk_bf16_f32 v112, v2, v3
	v_pk_mul_f32 v[2:3], v[0:1], v[118:119] op_sel_hi:[0,1]
	v_pk_mul_f32 v[2:3], v[8:9], v[2:3]
	v_cvt_pk_bf16_f32 v111, v4, v5
	v_cvt_pk_bf16_f32 v113, v2, v3
	v_pk_mul_f32 v[2:3], v[0:1], v[114:115] op_sel_hi:[0,1]
	v_pk_mul_f32 v[2:3], v[48:49], v[2:3]
	v_mov_b32_e32 v4, v1
	v_cvt_pk_bf16_f32 v114, v2, v3
	v_pk_mul_f32 v[2:3], v[0:1], v[116:117] op_sel_hi:[0,1]
	v_pk_mul_f32 v[2:3], v[50:51], v[2:3]
	v_mov_b32_e32 v5, v1
	v_cvt_pk_bf16_f32 v115, v2, v3
	v_pk_mul_f32 v[2:3], v[0:1], v[96:97] op_sel_hi:[0,1]
	v_pk_mul_f32 v[2:3], v[10:11], v[2:3]
	v_mov_b32_e32 v6, v1
	v_cvt_pk_bf16_f32 v116, v2, v3
	v_pk_mul_f32 v[2:3], v[0:1], v[92:93] op_sel_hi:[0,1]
	v_pk_mul_f32 v[2:3], v[12:13], v[2:3]
	v_mov_b32_e32 v7, v1
	v_cvt_pk_bf16_f32 v117, v2, v3
	v_pk_mul_f32 v[2:3], v[0:1], v[90:91] op_sel_hi:[0,1]
	v_pk_mul_f32 v[2:3], v[44:45], v[2:3]
	v_mov_b32_e32 v8, v1
	v_cvt_pk_bf16_f32 v118, v2, v3
	v_pk_mul_f32 v[2:3], v[0:1], v[88:89] op_sel_hi:[0,1]
	v_pk_mul_f32 v[2:3], v[46:47], v[2:3]
	v_mov_b32_e32 v9, v1
	v_cvt_pk_bf16_f32 v119, v2, v3
	v_pk_mul_f32 v[2:3], v[0:1], v[86:87] op_sel_hi:[0,1]
	v_pk_mul_f32 v[2:3], v[14:15], v[2:3]
	v_mov_b32_e32 v14, v1
	v_cvt_pk_bf16_f32 v120, v2, v3
	v_pk_mul_f32 v[2:3], v[0:1], v[84:85] op_sel_hi:[0,1]
	v_pk_mul_f32 v[2:3], v[16:17], v[2:3]
	v_mov_b32_e32 v15, v1
	v_cvt_pk_bf16_f32 v121, v2, v3
	v_pk_mul_f32 v[2:3], v[0:1], v[82:83] op_sel_hi:[0,1]
	v_pk_mul_f32 v[2:3], v[40:41], v[2:3]
	v_mov_b32_e32 v10, v1
	v_cvt_pk_bf16_f32 v122, v2, v3
	v_pk_mul_f32 v[2:3], v[0:1], v[80:81] op_sel_hi:[0,1]
	v_pk_mul_f32 v[2:3], v[42:43], v[2:3]
	v_mov_b32_e32 v11, v1
	v_cvt_pk_bf16_f32 v123, v2, v3
	v_pk_mul_f32 v[2:3], v[0:1], v[78:79] op_sel_hi:[0,1]
	v_pk_mul_f32 v[2:3], v[36:37], v[2:3]
	v_mov_b32_e32 v12, v1
	v_cvt_pk_bf16_f32 v124, v2, v3
	v_pk_mul_f32 v[2:3], v[0:1], v[76:77] op_sel_hi:[0,1]
	v_pk_mul_f32 v[2:3], v[38:39], v[2:3]
	v_mov_b32_e32 v13, v1
	v_cvt_pk_bf16_f32 v125, v2, v3
	v_pk_mul_f32 v[2:3], v[74:75], v[0:1] op_sel_hi:[1,0]
	v_mul_u32_u24_e32 v237, 0x90, v59
	v_pk_mul_f32 v[2:3], v[32:33], v[2:3]
	v_add_u32_e32 v239, v58, v139
	v_cvt_pk_bf16_f32 v126, v2, v3
	v_pk_mul_f32 v[2:3], v[72:73], v[0:1] op_sel_hi:[1,0]
	s_mov_b32 s13, 0
	v_pk_mul_f32 v[2:3], v[34:35], v[2:3]
	v_mov_b32_e32 v250, 0
	v_cvt_pk_bf16_f32 v127, v2, v3
	v_pk_mul_f32 v[2:3], v[70:71], v[0:1] op_sel_hi:[1,0]
	v_mov_b32_e32 v249, 0
	v_pk_mul_f32 v[2:3], v[18:19], v[2:3]
	s_nop 0
	v_cvt_pk_bf16_f32 v128, v2, v3
	v_pk_mul_f32 v[2:3], v[68:69], v[0:1] op_sel_hi:[1,0]
	s_nop 0
	v_pk_mul_f32 v[2:3], v[20:21], v[2:3]
	s_nop 0
	v_cvt_pk_bf16_f32 v129, v2, v3
	v_pk_mul_f32 v[2:3], v[22:23], v[0:1] op_sel_hi:[1,0]
	s_nop 0
	v_pk_mul_f32 v[2:3], v[28:29], v[2:3]
	s_nop 0
	v_cvt_pk_bf16_f32 v130, v2, v3
	v_pk_mul_f32 v[2:3], v[64:65], v[0:1] op_sel_hi:[1,0]
	s_nop 0
	v_pk_mul_f32 v[2:3], v[30:31], v[2:3]
	s_nop 0
	v_cvt_pk_bf16_f32 v131, v2, v3
	v_pk_mul_f32 v[2:3], v[62:63], v[0:1] op_sel_hi:[1,0]
	s_nop 0
	v_pk_mul_f32 v[2:3], v[24:25], v[2:3]
	s_nop 0
	v_cvt_pk_bf16_f32 v132, v2, v3
	v_pk_mul_f32 v[2:3], v[60:61], v[0:1] op_sel_hi:[1,0]
	v_and_b32_e32 v0, 19, v136
	v_pk_mul_f32 v[2:3], v[2:3], v[26:27]
	s_nop 0
	v_cvt_pk_bf16_f32 v133, v2, v3
	v_lshlrev_b32_e32 v2, 1, v136
	v_lshrrev_b32_e32 v3, 1, v136
	v_and_b32_e32 v2, 8, v2
	v_and_b32_e32 v3, 4, v3
	v_or3_b32 v0, v0, v2, v3
	v_mul_u32_u24_e32 v233, 0xd0, v0
	v_add_u32_e32 v0, s46, v138
	v_lshlrev_b64 v[2:3], 9, v[0:1]
	v_lshl_or_b32 v2, v137, 4, v2
	v_lshl_add_u64 v[240:241], s[38:39], 0, v[2:3]
	v_lshl_add_u64 v[2:3], s[46:47], 0, v[56:57]
	v_lshlrev_b64 v[2:3], 10, v[2:3]
	v_lshl_or_b32 v2, v135, 4, v2
	v_lshl_add_u32 v0, v135, 13, s8
	v_lshl_add_u64 v[242:243], s[42:43], 0, v[2:3]
	v_and_b32_e32 v0, 0xffff0000, v0
	v_lshlrev_b64 v[2:3], 7, v[56:57]
	v_lshl_add_u64 v[2:3], v[0:1], 0, v[2:3]
	v_add_lshl_u32 v0, s46, v134, 1
	v_and_or_b32 v2, v0, s12, v2
	v_lshl_add_u64 v[244:245], s[44:45], 0, v[2:3]
	v_mov_b32_e32 v0, v1
	v_mov_b32_e32 v2, v1
	v_mov_b32_e32 v3, v1
	v_mov_b64_e32 v[32:33], v[14:15]
	v_mov_b64_e32 v[30:31], v[12:13]
	v_mov_b64_e32 v[28:29], v[10:11]
	v_mov_b64_e32 v[26:27], v[8:9]
	v_mov_b64_e32 v[24:25], v[6:7]
	v_mov_b64_e32 v[22:23], v[4:5]
	v_mov_b64_e32 v[20:21], v[2:3]
	v_mov_b64_e32 v[18:19], v[0:1]
	v_mov_b64_e32 v[16:17], v[14:15]
	v_mov_b64_e32 v[14:15], v[12:13]
	v_mov_b64_e32 v[12:13], v[10:11]
	v_mov_b64_e32 v[10:11], v[8:9]
	v_mov_b64_e32 v[8:9], v[6:7]
	v_mov_b64_e32 v[6:7], v[4:5]
	v_mov_b64_e32 v[4:5], v[2:3]
	v_mov_b64_e32 v[2:3], v[0:1]
	v_mov_b32_e32 v212, 0xff800000
	v_mov_b32_e32 v213, 0xff800000
	v_mov_b32_e32 v34, 0
	v_mov_b32_e32 v35, 0
	v_mov_b32_e32 v36, 0
	v_mov_b32_e32 v37, 0
	v_mov_b32_e32 v38, 0
	v_mov_b32_e32 v39, 0
	v_mov_b32_e32 v40, 0
	v_mov_b32_e32 v41, 0
	v_mov_b32_e32 v42, 0
	v_mov_b32_e32 v43, 0
	v_mov_b32_e32 v44, 0
	v_mov_b32_e32 v45, 0
	v_mov_b32_e32 v46, 0
	v_mov_b32_e32 v47, 0
	v_mov_b32_e32 v48, 0
	v_mov_b32_e32 v49, 0
	s_cmp_eq_u64 s[40:41], 0
	s_cbranch_scc0 .Latt_head
	s_barrier

; #define LAS __attribute__((address_space(3)))
; __device__ __forceinline__ float shx32(float v, int lane) { return __int_as_float(__builtin_amdgcn_ds_bpermute((lane ^ 32) << 2, __float_as_int(v))); }
; template <bool MASKED>
; __device__ __forceinline__ void attn_step(const bf16x8 (&ka)[2][6], const bf16x8 (&va)[2][4], const bf16x8 (&qf)[6], int nvalid, int lane, f32x16& o0, f32x16& o1, float& mrun, float& lsum) {
;     ...
;     for (int s = 0; s < 6; ++s) { s0 = __builtin_amdgcn_mfma_f32_32x32x16_bf16(ka[0][s], qf[s], s0, 0, 0, 0); s1 = __builtin_amdgcn_mfma_f32_32x32x16_bf16(ka[1][s], qf[s], s1, 0, 0, 0); }
;     if (MASKED) {
; #pragma unroll
;         for (int i = 0; i < 16; ++i) { if (16 * (i >> 3) >= nvalid) s0[i] = -INFINITY; if (32 + 16 * (i >> 3) >= nvalid) s1[i] = -INFINITY; }
;     }
;     float mx = fmaxf(fmaxf(s0[0], s0[1]), s0[2]);
; #pragma unroll
;     for (int i = 3; i < 15; i += 2) mx = fmaxf(fmaxf(mx, s0[i]), s0[i + 1]);
;     mx = fmaxf(mx, s0[15]);
; #pragma unroll
;     for (int i = 0; i < 16; i += 2) mx = fmaxf(fmaxf(mx, s1[i]), s1[i + 1]);
;     if (__builtin_amdgcn_ballot_w64(mx > mrun + 8.0f) != 0ull) {
;         mx = fmaxf(mx, shx32(mx, lane));
;         const float mnew = fmaxf(mrun, mx);
;         const float alpha = __builtin_amdgcn_exp2f(mrun - mnew);
;         mrun = mnew; lsum *= alpha;
; #pragma unroll
;         for (int i = 0; i < 16; ++i) { o0[i] *= alpha; o1[i] *= alpha; }
;     }
; __device__ __forceinline__ void attn_item(const Params& p, int l, LAS unsigned char* lds, int b, int h, int J) {
;     ...
;             bf16x8 ka[2][6], va[2][4];
; #pragma unroll
;             for (int kb = 0; kb < 2; ++kb)
; #pragma unroll
;                 for (int s = 0; s < 6; ++s) ka[kb][s] = *(const LAS bf16x8*)(cur + rk + kb * 32 * KROW + 32 * s);
; #pragma unroll
;             for (int dvb = 0; dvb < 2; ++dvb)
; #pragma unroll
;                 for (int ks = 0; ks < 4; ++ks) va[dvb][ks] = *(const LAS bf16x8*)(cur + rv + dvb * 32 * VROW + 32 * ks);
;             __builtin_amdgcn_sched_barrier(0);
;             if (j < my_nt - 1) attn_step<false>(ka, va, qf, 64, lane, o0, o1, mrun, lsum); else attn_step<true>(ka, va, qf, 16, lane, o0, o1, mrun, lsum);
.Latt_nold:
	s_cmp_ge_i32 s13, s11
	s_cbranch_scc1 .Latt_skip
	s_bitcmp1_b32 s13, 0
	s_cselect_b32 s14, 0x5800, 0
	s_add_i32 s14, s14, 0
	v_add3_u32 v0, s14, v233, v236
	ds_read_b128 v[186:189], v0
	ds_read_b128 v[182:185], v0 offset:32
	ds_read_b128 v[178:181], v0 offset:64
	ds_read_b128 v[174:177], v0 offset:96
	ds_read_b128 v[170:173], v0 offset:128
	ds_read_b128 v[166:169], v0 offset:160
	ds_read_b128 v[50:53], v0 offset:6656
	ds_read_b128 v[206:209], v0 offset:6688
	ds_read_b128 v[202:205], v0 offset:6720
	ds_read_b128 v[198:201], v0 offset:6752
	ds_read_b128 v[194:197], v0 offset:6784
	ds_read_b128 v[190:193], v0 offset:6816
	v_add3_u32 v0, s14, v237, v236
	ds_read_b128 v[158:161], v0 offset:13312
	ds_read_b128 v[150:153], v0 offset:13344
	ds_read_b128 v[146:149], v0 offset:13376
	ds_read_b128 v[138:141], v0 offset:13408
	ds_read_b128 v[162:165], v0 offset:17920
	ds_read_b128 v[154:157], v0 offset:17952
	ds_read_b128 v[142:145], v0 offset:17984
	ds_read_b128 v[134:137], v0 offset:18016
	s_cmp_gt_i32 s13, s10
	s_cbranch_scc1 .Latt_masked
	s_waitcnt lgkmcnt(14)
	v_mfma_f32_32x32x16_bf16 v[66:81], v[186:189], v[110:113], v[34:49]
	v_mfma_f32_32x32x16_bf16 v[66:81], v[182:185], v[114:117], v[66:81]
	s_waitcnt lgkmcnt(13)
	v_mfma_f32_32x32x16_bf16 v[50:65], v[50:53], v[110:113], v[34:49]
	v_mfma_f32_32x32x16_bf16 v[66:81], v[178:181], v[118:121], v[66:81]
	s_waitcnt lgkmcnt(12)
	v_mfma_f32_32x32x16_bf16 v[50:65], v[206:209], v[114:117], v[50:65]
	v_mfma_f32_32x32x16_bf16 v[66:81], v[174:177], v[122:125], v[66:81]
	s_waitcnt lgkmcnt(11)
	v_mfma_f32_32x32x16_bf16 v[50:65], v[202:205], v[118:121], v[50:65]
	v_mfma_f32_32x32x16_bf16 v[66:81], v[170:173], v[126:129], v[66:81]
	s_waitcnt lgkmcnt(10)
	v_mfma_f32_32x32x16_bf16 v[50:65], v[198:201], v[122:125], v[50:65]
	v_mfma_f32_32x32x16_bf16 v[66:81], v[166:169], v[130:133], v[66:81]
	s_waitcnt lgkmcnt(9)
	v_mfma_f32_32x32x16_bf16 v[50:65], v[194:197], v[126:129], v[50:65]
	s_nop 9
	v_max3_f32 v0, v66, v67, v68
	v_max3_f32 v0, v0, v69, v70
	v_max3_f32 v0, v0, v71, v72
	v_max3_f32 v0, v0, v73, v74
	v_max3_f32 v0, v0, v75, v76
	s_waitcnt lgkmcnt(8)
	v_mfma_f32_32x32x16_bf16 v[50:65], v[190:193], v[130:133], v[50:65]
	v_max3_f32 v0, v0, v77, v78
	v_max3_f32 v0, v0, v79, v80
	v_max_f32_e32 v0, v0, v81
	s_nop 8
	v_max3_f32 v0, v0, v50, v51
	v_max3_f32 v0, v0, v52, v53
	v_max3_f32 v0, v0, v54, v55
	v_max3_f32 v0, v0, v56, v57
	v_max3_f32 v0, v0, v58, v59
	v_max3_f32 v0, v0, v60, v61
	v_max3_f32 v0, v0, v62, v63
	v_max3_f32 v0, v0, v64, v65
	s_cmp_lt_i32 s12, s5
	s_cbranch_scc0 .Latt_noe_main
	s_bitcmp1_b32 s12, 0
	s_cselect_b32 s14, 0x5800, 0
	v_add_u32_e32 v82, s14, v234
	s_waitcnt vmcnt(1)
	ds_write_b128 v82, v[98:101]
	v_add_u32_e32 v82, s14, v238
	s_waitcnt vmcnt(0)
	ds_write_b128 v82, v[102:105] offset:13312
	s_and_saveexec_b64 s[50:51], s[40:41]
	v_add_u32_e32 v82, s14, v239
	ds_write_b128 v82, v[106:109] offset:128
	s_or_b64 exec, exec, s[50:51]
.Latt_noe_main:
	s_waitcnt lgkmcnt(0)
	s_barrier
	v_cmp_gt_f32_e32 vcc, v0, v212
	s_cbranch_vccz .Latt_softmax
	ds_bpermute_b32 v82, v235, v0
	s_waitcnt lgkmcnt(0)
	v_max3_f32 v82, v0, v82, v213
	v_exp_f32_e64 v84, -v82
	v_add_f32_e32 v250, v250, v82
	v_mov_b32_e32 v212, 0x41000000
	v_mul_f32_e32 v249, v249, v84
	v_pk_mul_f32 v[32:33], v[32:33], v[84:85] op_sel_hi:[1,0]
	v_pk_mul_f32 v[30:31], v[30:31], v[84:85] op_sel_hi:[1,0]
	v_pk_mul_f32 v[28:29], v[28:29], v[84:85] op_sel_hi:[1,0]
	v_pk_mul_f32 v[26:27], v[26:27], v[84:85] op_sel_hi:[1,0]
	v_pk_mul_f32 v[24:25], v[24:25], v[84:85] op_sel_hi:[1,0]
	v_pk_mul_f32 v[22:23], v[22:23], v[84:85] op_sel_hi:[1,0]
	v_pk_mul_f32 v[20:21], v[20:21], v[84:85] op_sel_hi:[1,0]
	v_pk_mul_f32 v[18:19], v[18:19], v[84:85] op_sel_hi:[1,0]
	v_pk_mul_f32 v[16:17], v[16:17], v[84:85] op_sel_hi:[1,0]
	v_pk_mul_f32 v[14:15], v[14:15], v[84:85] op_sel_hi:[1,0]
	v_pk_mul_f32 v[12:13], v[12:13], v[84:85] op_sel_hi:[1,0]
	v_pk_mul_f32 v[10:11], v[10:11], v[84:85] op_sel_hi:[1,0]
	v_pk_mul_f32 v[8:9], v[8:9], v[84:85] op_sel_hi:[1,0]
	v_pk_mul_f32 v[6:7], v[6:7], v[84:85] op_sel_hi:[1,0]
	v_pk_mul_f32 v[4:5], v[4:5], v[84:85] op_sel_hi:[1,0]
	v_pk_mul_f32 v[2:3], v[2:3], v[84:85] op_sel_hi:[1,0]
	v_mov_b32_e32 v213, 0
	v_xor_b32_e32 v34, 0x80000000, v250
	v_sub_f32_e32 v66, v66, v82
	v_sub_f32_e32 v67, v67, v82
	v_sub_f32_e32 v68, v68, v82
	v_sub_f32_e32 v69, v69, v82
	v_sub_f32_e32 v70, v70, v82
	v_sub_f32_e32 v71, v71, v82
	v_sub_f32_e32 v72, v72, v82
	v_sub_f32_e32 v73, v73, v82
	v_sub_f32_e32 v74, v74, v82
	v_sub_f32_e32 v75, v75, v82
	v_sub_f32_e32 v76, v76, v82
	v_sub_f32_e32 v77, v77, v82
	v_sub_f32_e32 v78, v78, v82
	v_sub_f32_e32 v79, v79, v82
	v_sub_f32_e32 v80, v80, v82
	v_sub_f32_e32 v81, v81, v82
	v_sub_f32_e32 v50, v50, v82
	v_sub_f32_e32 v51, v51, v82
	v_sub_f32_e32 v52, v52, v82
	v_sub_f32_e32 v53, v53, v82
	v_sub_f32_e32 v54, v54, v82
	v_sub_f32_e32 v55, v55, v82
	v_sub_f32_e32 v56, v56, v82
	v_sub_f32_e32 v57, v57, v82
	v_sub_f32_e32 v58, v58, v82
	v_sub_f32_e32 v59, v59, v82
	v_sub_f32_e32 v60, v60, v82
	v_sub_f32_e32 v61, v61, v82
	v_sub_f32_e32 v62, v62, v82
	v_sub_f32_e32 v63, v63, v82
	v_sub_f32_e32 v64, v64, v82
	v_sub_f32_e32 v65, v65, v82
	v_mov_b32_e32 v35, v34
	v_mov_b32_e32 v36, v34
	v_mov_b32_e32 v37, v34
	v_mov_b32_e32 v38, v34
	v_mov_b32_e32 v39, v34
	v_mov_b32_e32 v40, v34
	v_mov_b32_e32 v41, v34
	v_mov_b32_e32 v42, v34
	v_mov_b32_e32 v43, v34
	v_mov_b32_e32 v44, v34
	v_mov_b32_e32 v45, v34
	v_mov_b32_e32 v46, v34
	v_mov_b32_e32 v47, v34
	v_mov_b32_e32 v48, v34
	v_mov_b32_e32 v49, v34
; __device__ __forceinline__ unsigned pk2(float a, float b) { f32x2 v = {a, b}; bf16x2_t r = __builtin_convertvector(v, bf16x2_t); return __builtin_bit_cast(unsigned, r); }
; template <bool MASKED>
; __device__ __forceinline__ void attn_step(const bf16x8 (&ka)[2][6], const bf16x8 (&va)[2][4], const bf16x8 (&qf)[6], int nvalid, int lane, f32x16& o0, f32x16& o1, float& mrun, float& lsum) {
;     ...
;     {
;         const f32x2 m2 = {mrun, mrun}; f32x2 acc2 = {0.f, 0.f};
; #pragma unroll
;         for (int i = 0; i < 16; i += 2) {
;             f32x2 a = (f32x2){s0[i], s0[i + 1]} - m2, c = (f32x2){s1[i], s1[i + 1]} - m2;
;             a.x = __builtin_amdgcn_exp2f(a.x); a.y = __builtin_amdgcn_exp2f(a.y); c.x = __builtin_amdgcn_exp2f(c.x); c.y = __builtin_amdgcn_exp2f(c.y);
;             acc2 = acc2 + a; acc2 = acc2 + c;
;             s0[i] = a.x; s0[i + 1] = a.y; s1[i] = c.x; s1[i + 1] = c.y;
;         }
;         lsum += acc2.x + acc2.y;
;     }
;     bf16x8 pf[4];
;     { u32x4 w;
;       w.x = pk2(s0[0], s0[1]); w.y = pk2(s0[2], s0[3]); w.z = pk2(s0[4], s0[5]); w.w = pk2(s0[6], s0[7]); pf[0] = __builtin_bit_cast(bf16x8, w);
;       w.x = pk2(s0[8], s0[9]); w.y = pk2(s0[10], s0[11]); w.z = pk2(s0[12], s0[13]); w.w = pk2(s0[14], s0[15]); pf[1] = __builtin_bit_cast(bf16x8, w);
;       w.x = pk2(s1[0], s1[1]); w.y = pk2(s1[2], s1[3]); w.z = pk2(s1[4], s1[5]); w.w = pk2(s1[6], s1[7]); pf[2] = __builtin_bit_cast(bf16x8, w);
;       w.x = pk2(s1[8], s1[9]); w.y = pk2(s1[10], s1[11]); w.z = pk2(s1[12], s1[13]); w.w = pk2(s1[14], s1[15]); pf[3] = __builtin_bit_cast(bf16x8, w); }
; #pragma unroll
;     for (int ks = 0; ks < 4; ++ks) { o0 = __builtin_amdgcn_mfma_f32_32x32x16_bf16(va[0][ks], pf[ks], o0, 0, 0, 0); o1 = __builtin_amdgcn_mfma_f32_32x32x16_bf16(va[1][ks], pf[ks], o1, 0, 0, 0); }
.Latt_softmax:
	v_exp_f32_e32 v66, v66
	v_exp_f32_e32 v67, v67
	v_exp_f32_e32 v68, v68
	v_exp_f32_e32 v69, v69
	v_exp_f32_e32 v70, v70
	v_exp_f32_e32 v71, v71
	v_cvt_pk_bf16_f32 v82, v66, v67
	v_exp_f32_e32 v72, v72
	v_cvt_pk_bf16_f32 v83, v68, v69
	v_exp_f32_e32 v73, v73
	v_cvt_pk_bf16_f32 v84, v70, v71
	v_add_f32_e32 v190, v66, v67
	v_add_f32_e32 v191, v68, v69
	v_cvt_pk_bf16_f32 v85, v72, v73
	v_exp_f32_e32 v74, v74
	v_exp_f32_e32 v75, v75
	v_mfma_f32_32x32x16_bf16 v[18:33], v[158:161], v[82:85], v[18:33]
	v_exp_f32_e32 v76, v76
	v_add_f32_e32 v190, v190, v70
	v_add_f32_e32 v191, v191, v71
	v_exp_f32_e32 v77, v77
	v_mfma_f32_32x32x16_bf16 v[2:17], v[162:165], v[82:85], v[2:17]
	v_exp_f32_e32 v78, v78
	v_add_f32_e32 v190, v190, v72
	v_add_f32_e32 v191, v191, v73
	v_exp_f32_e32 v79, v79
	v_cvt_pk_bf16_f32 v86, v74, v75
	v_exp_f32_e32 v80, v80
	v_cvt_pk_bf16_f32 v87, v76, v77
	v_exp_f32_e32 v81, v81
	v_cvt_pk_bf16_f32 v88, v78, v79
	v_add_f32_e32 v190, v190, v74
	v_add_f32_e32 v191, v191, v75
	v_cvt_pk_bf16_f32 v89, v80, v81
	v_exp_f32_e32 v50, v50
	v_exp_f32_e32 v51, v51
	v_mfma_f32_32x32x16_bf16 v[18:33], v[150:153], v[86:89], v[18:33]
	v_exp_f32_e32 v52, v52
	v_add_f32_e32 v190, v190, v76
	v_add_f32_e32 v191, v191, v77
	v_exp_f32_e32 v53, v53
	v_mfma_f32_32x32x16_bf16 v[2:17], v[154:157], v[86:89], v[2:17]
	v_exp_f32_e32 v54, v54
	v_add_f32_e32 v190, v190, v78
	v_add_f32_e32 v191, v191, v79
	v_exp_f32_e32 v55, v55
	v_cvt_pk_bf16_f32 v90, v50, v51
	v_exp_f32_e32 v56, v56
	v_cvt_pk_bf16_f32 v91, v52, v53
	v_exp_f32_e32 v57, v57
	v_cvt_pk_bf16_f32 v92, v54, v55
	v_add_f32_e32 v190, v190, v80
	v_add_f32_e32 v191, v191, v81
	v_cvt_pk_bf16_f32 v93, v56, v57
	v_exp_f32_e32 v58, v58
	v_exp_f32_e32 v59, v59
	v_mfma_f32_32x32x16_bf16 v[18:33], v[146:149], v[90:93], v[18:33]
	v_exp_f32_e32 v60, v60
	v_add_f32_e32 v190, v190, v50
	v_add_f32_e32 v191, v191, v51
	v_exp_f32_e32 v61, v61
	v_mfma_f32_32x32x16_bf16 v[2:17], v[142:145], v[90:93], v[2:17]
	v_exp_f32_e32 v62, v62
	v_add_f32_e32 v190, v190, v52
	v_add_f32_e32 v191, v191, v53
	v_exp_f32_e32 v63, v63
	v_cvt_pk_bf16_f32 v94, v58, v59
	v_exp_f32_e32 v64, v64
	v_cvt_pk_bf16_f32 v95, v60, v61
	v_exp_f32_e32 v65, v65
	v_cvt_pk_bf16_f32 v96, v62, v63
	v_add_f32_e32 v190, v190, v54
	v_add_f32_e32 v191, v191, v55
	v_cvt_pk_bf16_f32 v97, v64, v65
	v_add_f32_e32 v190, v190, v56
	v_add_f32_e32 v191, v191, v57
	v_mfma_f32_32x32x16_bf16 v[18:33], v[138:141], v[94:97], v[18:33]
	v_add_f32_e32 v190, v190, v58
	v_add_f32_e32 v191, v191, v59
	v_add_f32_e32 v190, v190, v60
	v_add_f32_e32 v191, v191, v61
	v_mfma_f32_32x32x16_bf16 v[2:17], v[134:137], v[94:97], v[2:17]
	v_add_f32_e32 v190, v190, v62
	v_add_f32_e32 v191, v191, v63
	v_add_f32_e32 v190, v190, v64
	v_add_f32_e32 v191, v191, v65
	v_add_f32_e32 v190, v190, v191
	v_add_f32_e32 v249, v249, v190
	v_mov_b64_e32 v[200:201], v[216:217]
	s_branch .Latt_end
.Latt_masked:
	v_add_f32_e32 v212, 0x41000000, v250
	s_cmp_lt_i32 s12, s5
	s_cbranch_scc0 .Latt_noe_mask
	s_bitcmp1_b32 s12, 0
	s_cselect_b32 s14, 0x5800, 0
	v_add_u32_e32 v0, s14, v234
	s_waitcnt vmcnt(1)
	ds_write_b128 v0, v[98:101]
	v_add_u32_e32 v0, s14, v238
	s_waitcnt vmcnt(0)
	ds_write_b128 v0, v[102:105] offset:13312
	s_and_saveexec_b64 s[50:51], s[40:41]
	v_add_u32_e32 v0, s14, v239
	ds_write_b128 v0, v[106:109] offset:128
	s_or_b64 exec, exec, s[50:51]
